# stagger of waves 4-7 extended over all 16 K-tiles of the gate and w_out K-loops (own 16-trip loop with guarded DMA), branch K-loop keeps rejoin before the peeled tiles
# baseline (speedup 1.0000x reference)
; DI void wait_vm0() { asm volatile("s_waitcnt vmcnt(0)" ::: "memory"); }
; template <int MB, bool SWAP>
; DI void gemm_kloop(f32x16 (&acc)[MB][2], const h16* __restrict__ A, int lda, const h16* __restrict__ B, int ldb, int K, char* lds) {
;     ...
;   for (int kt = 0; kt < nk; ++kt) {
;     if (kt + 1 < nk) { if (MB == 2) asm volatile("s_waitcnt vmcnt(6)" ::: "memory"); else asm volatile("s_waitcnt vmcnt(5)" ::: "memory"); }
;     else wait_vm0();
;     __syncthreads();
;     const char* s = lds + cur * STAGE;
;     const int nbuf = cur == 0 ? 2 : cur - 1;
;     const bool more = kt + 2 < nk;
.Lstg40_top:
	s_mul_i32 s25, s24, 0xc000
	s_add_i32 s33, s25, 0
	s_add_i32 s25, s25, 0xffff4000
	s_cmp_lg_u32 s24, 0
	s_cselect_b32 s25, s25, 0x18000
	v_add_u32_e32 v51, s25, v10
	v_add_u32_e32 v11, s33, v6
	v_add_u32_e32 v50, s33, v4
	v_add_u32_e32 v48, 0x2000, v51
	v_lshl_add_u64 v[44:45], v[0:1], 0, s[80:81]
	v_readfirstlane_b32 s25, v51
	v_lshl_add_u64 v[46:47], v[44:45], 0, s[52:53]
	v_lshl_add_u64 v[44:45], v[44:45], 0, s[90:91]
	s_mov_b32 m0, s25
	v_readfirstlane_b32 s25, v48
	s_cmp_eq_u32 s80, 0x780
	s_cbranch_scc1 .Lstg40_w0
	s_waitcnt vmcnt(6)
	s_branch .Lstg40_w1

; DI void wait_vm0() { asm volatile("s_waitcnt vmcnt(0)" ::: "memory"); }
; template <int MB, bool SWAP>
; DI void gemm_kloop(f32x16 (&acc)[MB][2], const h16* __restrict__ A, int lda, const h16* __restrict__ B, int ldb, int K, char* lds) {
;     ...
;   for (int kt = 0; kt < nk; ++kt) {
;     if (kt + 1 < nk) { if (MB == 2) asm volatile("s_waitcnt vmcnt(6)" ::: "memory"); else asm volatile("s_waitcnt vmcnt(5)" ::: "memory"); }
;     else wait_vm0();
;     __syncthreads();
;     const char* s = lds + cur * STAGE;
;     const int nbuf = cur == 0 ? 2 : cur - 1;
;     const bool more = kt + 2 < nk;
;     half8 af[2][MB], bf[2][2];
; #pragma unroll
;     for (int mb = 0; mb < MB; ++mb) af[0][mb] = *(const half8*)(s + a_rd + mb * 4096 + (((0 + hh) ^ sw) * 16));
; #pragma unroll
;     for (int nb = 0; nb < 2; ++nb) bf[0][nb] = *(const half8*)(s + b_rd + nb * 4096 + (((0 + hh) ^ sw) * 16));
; #pragma unroll
;     for (int ks = 0; ks < 4; ++ks) {
;       if (ks < 3) {
; #pragma unroll
;         for (int mb = 0; mb < MB; ++mb) af[(ks + 1) & 1][mb] = *(const half8*)(s + a_rd + mb * 4096 + (((2 * (ks + 1) + hh) ^ sw) * 16));
; #pragma unroll
;         for (int nb = 0; nb < 2; ++nb) bf[(ks + 1) & 1][nb] = *(const half8*)(s + b_rd + nb * 4096 + (((2 * (ks + 1) + hh) ^ sw) * 16));
;       }
;       if (more) {
;         if (2 * ks < NP) piece(2 * ks, kt + 2, nbuf);
;         if (2 * ks + 1 < NP) piece(2 * ks + 1, kt + 2, nbuf);
;       }
;       __builtin_amdgcn_sched_barrier(0);
;       __builtin_amdgcn_s_setprio(1);
; #pragma unroll
;       for (int mb = 0; mb < MB; ++mb)
; #pragma unroll
;         for (int nb = 0; nb < 2; ++nb)
;           acc[mb][nb] = SWAP ? __builtin_amdgcn_mfma_f32_32x32x16_f16(bf[ks & 1][nb], af[ks & 1][mb], acc[mb][nb], 0, 0, 0)
;                              : __builtin_amdgcn_mfma_f32_32x32x16_f16(af[ks & 1][mb], bf[ks & 1][nb], acc[mb][nb], 0, 0, 0);
;       __builtin_amdgcn_s_setprio(0);
;       __builtin_amdgcn_sched_barrier(0);
;     }
.Lstg40_w1:
	s_waitcnt lgkmcnt(0)
	s_barrier
	s_cmp_eq_u32 s80, 0
	s_cbranch_scc1 .Lstg40_skip
	s_setprio 1
	v_mfma_f32_32x32x16_f16 v[112:127], v[20:23], v[12:15], v[112:127]
	v_mfma_f32_32x32x16_f16 v[96:111], v[24:27], v[12:15], v[96:111]
	v_mfma_f32_32x32x16_f16 v[80:95], v[20:23], v[16:19], v[80:95]
	v_mfma_f32_32x32x16_f16 v[64:79], v[24:27], v[16:19], v[64:79]
	v_mfma_f32_32x32x16_f16 v[112:127], v[36:39], v[28:31], v[112:127]
	v_mfma_f32_32x32x16_f16 v[96:111], v[40:43], v[28:31], v[96:111]
	v_mfma_f32_32x32x16_f16 v[80:95], v[36:39], v[32:35], v[80:95]
	v_mfma_f32_32x32x16_f16 v[64:79], v[40:43], v[32:35], v[64:79]
	s_setprio 0
.Lstg40_skip:
	v_add_u32_e32 v16, v11, v9
	v_add_u32_e32 v24, v50, v9
	v_add_u32_e32 v32, v11, v8
	v_add_u32_e32 v40, v50, v8
	ds_read_b128 v[12:15], v16
	ds_read_b128 v[16:19], v16 offset:4096
	ds_read_b128 v[20:23], v24 offset:16384
	ds_read_b128 v[24:27], v24 offset:20480
	ds_read_b128 v[28:31], v32
	ds_read_b128 v[32:35], v32 offset:4096
	ds_read_b128 v[36:39], v40 offset:16384
	ds_read_b128 v[40:43], v40 offset:20480
	s_cmp_lt_u32 s80, 0x700
	s_cbranch_scc0 .Lstg40_d0
	global_load_lds_dwordx4 v[44:45], off
	s_mov_b32 m0, s25
	v_lshl_add_u64 v[44:45], v[2:3], 0, s[80:81]
	global_load_lds_dwordx4 v[46:47], off
	v_lshl_add_u64 v[46:47], v[44:45], 0, s[72:73]
.Lstg40_d0:
	s_setprio 1
	s_waitcnt lgkmcnt(0)
	v_mfma_f32_32x32x16_f16 v[112:127], v[20:23], v[12:15], v[112:127]
	v_mfma_f32_32x32x16_f16 v[96:111], v[24:27], v[12:15], v[96:111]
	v_mfma_f32_32x32x16_f16 v[80:95], v[20:23], v[16:19], v[80:95]
	v_mfma_f32_32x32x16_f16 v[64:79], v[24:27], v[16:19], v[64:79]
	s_setprio 0
	v_add_u32_e32 v53, 0x4000, v51
	v_add_u32_e32 v52, 0x6000, v51
	v_readfirstlane_b32 s25, v53
	v_add_u32_e32 v16, v11, v7
	v_add_u32_e32 v24, v50, v7
	s_mov_b32 m0, s25
	v_readfirstlane_b32 s25, v52
	ds_read_b128 v[12:15], v16
	ds_read_b128 v[16:19], v16 offset:4096
	ds_read_b128 v[20:23], v24 offset:16384
	ds_read_b128 v[24:27], v24 offset:20480
	v_lshl_add_u64 v[48:49], v[44:45], 0, s[88:89]
	s_cmp_lt_u32 s80, 0x700
	s_cbranch_scc0 .Lstg40_d1
	global_load_lds_dwordx4 v[46:47], off
	s_mov_b32 m0, s25
	s_nop 0
	global_load_lds_dwordx4 v[48:49], off
.Lstg40_d1:
	s_setprio 1
	v_mfma_f32_32x32x16_f16 v[112:127], v[36:39], v[28:31], v[112:127]
	v_mfma_f32_32x32x16_f16 v[96:111], v[40:43], v[28:31], v[96:111]
	v_mfma_f32_32x32x16_f16 v[80:95], v[36:39], v[32:35], v[80:95]
	v_mfma_f32_32x32x16_f16 v[64:79], v[40:43], v[32:35], v[64:79]
	s_setprio 0
	v_add_u32_e32 v11, v11, v5
	ds_read_b128 v[28:31], v11
	ds_read_b128 v[32:35], v11 offset:4096
	v_add_u32_e32 v11, v50, v5
	v_add_u32_e32 v48, 0x8000, v51
	ds_read_b128 v[36:39], v11 offset:16384
	ds_read_b128 v[40:43], v11 offset:20480
	v_add_u32_e32 v11, 0xa000, v51
	v_readfirstlane_b32 s25, v48
	v_lshl_add_u64 v[46:47], v[44:45], 0, s[34:35]
	v_lshl_add_u64 v[44:45], v[44:45], 0, s[68:69]
	s_mov_b32 m0, s25
	v_readfirstlane_b32 s25, v11
	s_cmp_lt_u32 s80, 0x700
	s_cbranch_scc0 .Lstg40_d2
	global_load_lds_dwordx4 v[44:45], off
	s_mov_b32 m0, s25
	s_nop 0
	global_load_lds_dwordx4 v[46:47], off
.Lstg40_d2:
	s_add_i32 s25, s24, 1
	s_cmp_lg_u32 s24, 2
	s_cselect_b32 s24, s25, 0
	s_add_u32 s80, s80, 0x80
	s_addc_u32 s81, s81, 0
	s_cmp_eq_u32 s80, 0x800
	s_cbranch_scc0 .Lstg40_top
	s_waitcnt lgkmcnt(0)
	s_setprio 1
	v_mfma_f32_32x32x16_f16 v[112:127], v[20:23], v[12:15], v[112:127]
	v_mfma_f32_32x32x16_f16 v[96:111], v[24:27], v[12:15], v[96:111]
	v_mfma_f32_32x32x16_f16 v[80:95], v[20:23], v[16:19], v[80:95]
	v_mfma_f32_32x32x16_f16 v[64:79], v[24:27], v[16:19], v[64:79]
	v_mfma_f32_32x32x16_f16 v[112:127], v[36:39], v[28:31], v[112:127]
	v_mfma_f32_32x32x16_f16 v[96:111], v[40:43], v[28:31], v[96:111]
	v_mfma_f32_32x32x16_f16 v[80:95], v[36:39], v[32:35], v[80:95]
	v_mfma_f32_32x32x16_f16 v[64:79], v[40:43], v[32:35], v[64:79]
	s_setprio 0
	s_cmp_eq_u32 s45, 1
	s_cselect_b32 s24, s12, 0x1ba66000
	s_cmp_lg_u32 s45, 0
	s_cselect_b32 s24, s24, 0x10f66000
	s_add_i32 s25, 0, 0x18000
	s_mov_b32 vcc_hi, 0
	s_branch .Lstg40_end

; DI void wait_vm0() { asm volatile("s_waitcnt vmcnt(0)" ::: "memory"); }
; DI int otid() { int t = threadIdx.x; asm volatile("" : "+v"(t)); return t; }
; template <int MB, bool SWAP>
; DI void gemm_kloop(f32x16 (&acc)[MB][2], const h16* __restrict__ A, int lda, const h16* __restrict__ B, int ldb, int K, char* lds) {
;     ...
;   const int tid = otid(), w = tid >> 6, lane = tid & 63;
;   const int wr = w >> 2, wc = w & 3;
;   const int lrow = w * 8 + (lane >> 3), pch = lane & 7;
;   const int gch = pch ^ ((lrow >> 1) & 7);
;   const unsigned voa = (unsigned)(lrow * lda + gch * 8) * 2u, vob = (unsigned)(lrow * ldb + gch * 8) * 2u;
;   const int lofs = lrow * 128 + pch * 16;
;   const int r32 = lane & 31, hh = lane >> 5, sw = (r32 >> 1) & 7;
;   const int a_rd = (wr * 32 * MB + r32) * 128;
;   const int b_rd = A_BYTES + (wc * 64 + r32) * 128;
;   const int nk = K >> 6;
;   constexpr int NP = MB + 4;
;   auto piece = [&](int p, int kt, int buf) {
;     char* s = lds + buf * STAGE;
;     if (p < MB) __builtin_amdgcn_global_load_lds((const unsigned*)((const char*)(A + (size_t)p * 64 * lda + kt * 64) + voa), (unsigned*)(s + p * 8192 + lofs), 16, 0, 0);
;     else __builtin_amdgcn_global_load_lds((const unsigned*)((const char*)(B + (size_t)(p - MB) * 64 * ldb + kt * 64) + vob), (unsigned*)(s + A_BYTES + (p - MB) * 8192 + lofs), 16, 0, 0);
;   };
;   wait_vm0();
; #pragma unroll
;   for (int p = 0; p < NP; ++p) piece(p, 0, 0);
; #pragma unroll
;   for (int p = 0; p < NP; ++p) piece(p, 1, 1);
; template <int MB>
; DI void merge_tile(const Params& P, int layer, size_t row0, int nt, char* smem) {
;     ...
;     zero_acc<MB>(pa2);
;     gemm_kloop<MB, true>(pa2, yn + row0 * LDY, LDY, wbrT + (size_t)(n * 1024 + nt * 256) * LDY, LDY, WB, smem);
.Lstg40_end:
	v_mov_b32_e32 v6, v208
	s_barrier
	s_add_u32 s52, s3, s24
	v_ashrrev_i32_e32 v7, 3, v6
	v_bfe_u32 v8, v6, 3, 3
	v_and_or_b32 v0, v7, -8, v8
	v_lshrrev_b32_e32 v1, 1, v0
	v_xor_b32_e32 v1, v1, v6
	v_lshlrev_b32_e32 v1, 3, v1
	v_mul_lo_u32 v2, v0, s13
	v_and_b32_e32 v9, 56, v1
	v_or_b32_e32 v1, v9, v2
	v_lshlrev_b32_e32 v128, 1, v1
	v_lshlrev_b32_e32 v1, 4, v6
	v_and_b32_e32 v1, 0x70, v1
	v_lshl_or_b32 v10, v0, 7, v1
	s_addc_u32 s53, s2, 0
	s_or_b32 s25, vcc_lo, s71
	v_add_u32_e32 v205, 0, v10
	s_mul_i32 s84, s25, 0x240
	v_readfirstlane_b32 s25, v205
	s_waitcnt vmcnt(0)
	s_mov_b32 m0, s25
	v_add_u32_e32 v13, 0x2000, v205
	v_lshl_add_u64 v[2:3], s[52:53], 0, v[128:129]
	global_load_lds_dwordx4 v128, s[52:53]
	s_mov_b64 s[52:53], 0x12000
	v_readfirstlane_b32 s25, v13
	s_lshl_b64 s[54:55], s[84:85], 1
	v_lshl_add_u64 v[4:5], v[2:3], 0, s[52:53]
	s_mov_b32 m0, s25
	s_add_u32 s54, s75, s54
	v_and_b32_e32 v0, 31, v6
	v_lshrrev_b32_e32 v1, 2, v6
	global_load_lds_dwordx4 v[4:5], off
	v_add_u32_e32 v4, 0x4000, v205
	s_addc_u32 s55, s76, s55
	v_and_or_b32 v12, v1, s7, v0
	v_lshlrev_b32_e32 v0, 7, v6
	v_readfirstlane_b32 s25, v4
	v_add_u32_e32 v13, 0x6000, v205
	v_and_b32_e32 v199, 0x6f80, v0
	v_lshl_add_u64 v[0:1], s[54:55], 0, v[128:129]
	s_mov_b32 m0, s25
	v_readfirstlane_b32 s25, v13
	v_add_u32_e32 v13, 0x8000, v205
	global_load_lds_dwordx4 v128, s[54:55]
	v_lshl_add_u64 v[4:5], v[0:1], 0, s[52:53]
	s_mov_b32 m0, s25
	s_mov_b64 s[52:53], 0x24000
	v_readfirstlane_b32 s25, v13
	v_add_u32_e32 v13, 0xa000, v205
	global_load_lds_dwordx4 v[4:5], off
	v_lshl_add_u64 v[4:5], v[0:1], 0, s[52:53]
	s_mov_b32 m0, s25
	s_mov_b64 s[52:53], 0x36000
	v_readfirstlane_b32 s25, v13
	v_lshlrev_b32_e32 v204, 7, v12
	v_add_u32_e32 v12, 0xc000, v205
	global_load_lds_dwordx4 v[4:5], off
	v_lshl_add_u64 v[4:5], v[0:1], 0, s[52:53]
	s_mov_b32 m0, s25
	v_readfirstlane_b32 s25, v12
	global_load_lds_dwordx4 v[4:5], off
	v_lshl_add_u64 v[4:5], v[2:3], 0, s[22:23]
	s_mov_b32 m0, s25
	s_mov_b64 s[52:53], 0x12080
	global_load_lds_dwordx4 v[4:5], off
	v_add_u32_e32 v4, 0xe000, v205
	v_lshl_add_u64 v[2:3], v[2:3], 0, s[52:53]
	v_readfirstlane_b32 s25, v4
	v_add_u32_e32 v4, s8, v10
	s_mov_b32 m0, s25
	v_readfirstlane_b32 s25, v4
	v_add_u32_e32 v4, s9, v10
	global_load_lds_dwordx4 v[2:3], off
	v_lshl_add_u64 v[2:3], v[0:1], 0, s[22:23]
	s_mov_b32 m0, s25
	v_readfirstlane_b32 s25, v4
	v_add_u32_e32 v4, s79, v10
	global_load_lds_dwordx4 v[2:3], off
	v_lshl_add_u64 v[2:3], v[0:1], 0, s[52:53]
	s_mov_b32 m0, s25
	s_mov_b64 s[52:53], 0x24080
	v_readfirstlane_b32 s25, v4
	global_load_lds_dwordx4 v[2:3], off
	v_lshl_add_u64 v[2:3], v[0:1], 0, s[52:53]
	s_mov_b32 m0, s25
	s_mov_b64 s[52:53], 0x36080
	global_load_lds_dwordx4 v[2:3], off
	v_add_u32_e32 v2, s10, v10
	v_lshl_add_u64 v[0:1], v[0:1], 0, s[52:53]
	v_readfirstlane_b32 s25, v2
	s_mov_b32 m0, s25
	v_lshrrev_b32_e32 v11, 1, v6
	global_load_lds_dwordx4 v[0:1], off
	v_bfe_u32 v13, v6, 5, 1
	v_bfe_u32 v0, v6, 1, 3
	v_bitop3_b32 v1, v13, v11, 7 bitop3:0x78
	v_lshlrev_b32_e32 v203, 4, v1
	v_bitop3_b32 v1, v13, v0, 2 bitop3:0x36
	v_lshlrev_b32_e32 v202, 4, v1
	v_bitop3_b32 v1, v13, v0, 4 bitop3:0x36
	v_bitop3_b32 v0, v13, v0, 6 bitop3:0x36
	v_lshlrev_b32_e32 v200, 4, v0
	v_lshrrev_b32_e32 v0, 3, v7
	v_mul_lo_u32 v0, v0, s14
	v_mad_u32_u24 v0, v8, s13, v0
	v_or_b32_e32 v0, v0, v9
	s_add_u32 s24, s70, s24
	v_lshlrev_b32_e32 v128, 1, v0
	s_addc_u32 s25, s44, 0
	v_mov_b32_e32 v0, 0
	v_lshlrev_b32_e32 v201, 4, v1
	v_lshl_add_u64 v[186:187], s[24:25], 0, v[128:129]
	v_lshl_add_u64 v[188:189], s[40:41], 0, v[128:129]
	s_mov_b64 s[80:81], 0
	v_mov_b32_e32 v1, v0
	v_mov_b32_e32 v2, v0
	v_mov_b32_e32 v3, v0
	v_mov_b32_e32 v4, v0
	v_mov_b32_e32 v5, v0
	v_mov_b32_e32 v6, v0
	v_mov_b32_e32 v7, v0
	v_mov_b32_e32 v8, v0
	v_mov_b32_e32 v9, v0
	v_mov_b32_e32 v10, v0
	v_mov_b32_e32 v11, v0
	v_mov_b32_e32 v12, v0
	v_mov_b32_e32 v13, v0
	v_mov_b32_e32 v14, v0
	v_mov_b32_e32 v15, v0
	v_mov_b32_e32 v16, v0
	v_mov_b32_e32 v17, v0
	v_mov_b32_e32 v18, v0
	v_mov_b32_e32 v19, v0
	v_mov_b32_e32 v20, v0
	v_mov_b32_e32 v21, v0
	v_mov_b32_e32 v22, v0
	v_mov_b32_e32 v23, v0
	v_mov_b32_e32 v24, v0
	v_mov_b32_e32 v25, v0
	v_mov_b32_e32 v26, v0
	v_mov_b32_e32 v27, v0
	v_mov_b32_e32 v28, v0
	v_mov_b32_e32 v29, v0
	v_mov_b32_e32 v30, v0
	v_mov_b32_e32 v31, v0
	v_mov_b32_e32 v32, v0
	v_mov_b32_e32 v33, v0
	v_mov_b32_e32 v34, v0
	v_mov_b32_e32 v35, v0
	v_mov_b32_e32 v36, v0
	v_mov_b32_e32 v37, v0
	v_mov_b32_e32 v38, v0
	v_mov_b32_e32 v39, v0
	v_mov_b32_e32 v40, v0
	v_mov_b32_e32 v41, v0
	v_mov_b32_e32 v42, v0
	v_mov_b32_e32 v43, v0
	v_mov_b32_e32 v44, v0
	v_mov_b32_e32 v45, v0
	v_mov_b32_e32 v46, v0
	v_mov_b32_e32 v47, v0
	v_mov_b32_e32 v48, v0
	v_mov_b32_e32 v49, v0
	v_mov_b32_e32 v50, v0
	v_mov_b32_e32 v51, v0
	v_mov_b32_e32 v52, v0
	v_mov_b32_e32 v53, v0
	v_mov_b32_e32 v54, v0
	v_mov_b32_e32 v55, v0
	v_mov_b32_e32 v56, v0
	v_mov_b32_e32 v57, v0
	v_mov_b32_e32 v58, v0
	v_mov_b32_e32 v59, v0
	v_mov_b32_e32 v60, v0
	v_mov_b32_e32 v61, v0
	v_mov_b32_e32 v62, v0
	v_mov_b32_e32 v63, v0
	s_mov_b64 s[52:53], 0x1188100
	v_readfirstlane_b32 s25, v208
	s_nop 0
	s_lshr_b32 s25, s25, 8
	s_cmp_lg_u32 s25, 0
	s_cbranch_scc1 .Lstg42_top

; DI void wait_vm0() { asm volatile("s_waitcnt vmcnt(0)" ::: "memory"); }
; template <int MB, bool SWAP>
; DI void gemm_kloop(f32x16 (&acc)[MB][2], const h16* __restrict__ A, int lda, const h16* __restrict__ B, int ldb, int K, char* lds) {
;     ...
;   for (int kt = 0; kt < nk; ++kt) {
;     if (kt + 1 < nk) { if (MB == 2) asm volatile("s_waitcnt vmcnt(6)" ::: "memory"); else asm volatile("s_waitcnt vmcnt(5)" ::: "memory"); }
;     else wait_vm0();
;     __syncthreads();
;     const char* s = lds + cur * STAGE;
;     const int nbuf = cur == 0 ? 2 : cur - 1;
;     const bool more = kt + 2 < nk;
.Lstg723_top:
	s_mul_i32 s24, s3, 0xc000
	s_add_i32 s25, s24, 0
	s_add_i32 s24, s24, 0xffff4000
	s_cmp_lg_u32 s3, 0
	s_cselect_b32 s24, s24, 0x18000
	v_add_u32_e32 v115, s24, v74
	v_add_u32_e32 v75, s25, v70
	v_add_u32_e32 v114, s25, v68
	v_add_u32_e32 v112, 0x2000, v115
	v_lshl_add_u64 v[108:109], v[64:65], 0, s[50:51]
	v_readfirstlane_b32 s24, v115
	v_lshl_add_u64 v[110:111], v[108:109], 0, s[54:55]
	v_lshl_add_u64 v[108:109], v[108:109], 0, s[56:57]
	s_mov_b32 m0, s24
	v_readfirstlane_b32 s24, v112
	s_cmp_eq_u32 s50, 0x780
	s_cbranch_scc1 .Lstg723_w0
	s_waitcnt vmcnt(6)
	s_branch .Lstg723_w1

; DI void wait_vm0() { asm volatile("s_waitcnt vmcnt(0)" ::: "memory"); }
; template <int MB, bool SWAP>
; DI void gemm_kloop(f32x16 (&acc)[MB][2], const h16* __restrict__ A, int lda, const h16* __restrict__ B, int ldb, int K, char* lds) {
;     ...
;   for (int kt = 0; kt < nk; ++kt) {
;     if (kt + 1 < nk) { if (MB == 2) asm volatile("s_waitcnt vmcnt(6)" ::: "memory"); else asm volatile("s_waitcnt vmcnt(5)" ::: "memory"); }
;     else wait_vm0();
;     __syncthreads();
;     const char* s = lds + cur * STAGE;
;     const int nbuf = cur == 0 ? 2 : cur - 1;
;     const bool more = kt + 2 < nk;
;     half8 af[2][MB], bf[2][2];
; #pragma unroll
;     for (int mb = 0; mb < MB; ++mb) af[0][mb] = *(const half8*)(s + a_rd + mb * 4096 + (((0 + hh) ^ sw) * 16));
; #pragma unroll
;     for (int nb = 0; nb < 2; ++nb) bf[0][nb] = *(const half8*)(s + b_rd + nb * 4096 + (((0 + hh) ^ sw) * 16));
; #pragma unroll
;     for (int ks = 0; ks < 4; ++ks) {
;       if (ks < 3) {
; #pragma unroll
;         for (int mb = 0; mb < MB; ++mb) af[(ks + 1) & 1][mb] = *(const half8*)(s + a_rd + mb * 4096 + (((2 * (ks + 1) + hh) ^ sw) * 16));
; #pragma unroll
;         for (int nb = 0; nb < 2; ++nb) bf[(ks + 1) & 1][nb] = *(const half8*)(s + b_rd + nb * 4096 + (((2 * (ks + 1) + hh) ^ sw) * 16));
;       }
;       if (more) {
;         if (2 * ks < NP) piece(2 * ks, kt + 2, nbuf);
;         if (2 * ks + 1 < NP) piece(2 * ks + 1, kt + 2, nbuf);
;       }
;       __builtin_amdgcn_sched_barrier(0);
;       __builtin_amdgcn_s_setprio(1);
; #pragma unroll
;       for (int mb = 0; mb < MB; ++mb)
; #pragma unroll
;         for (int nb = 0; nb < 2; ++nb)
;           acc[mb][nb] = SWAP ? __builtin_amdgcn_mfma_f32_32x32x16_f16(bf[ks & 1][nb], af[ks & 1][mb], acc[mb][nb], 0, 0, 0)
;                              : __builtin_amdgcn_mfma_f32_32x32x16_f16(af[ks & 1][mb], bf[ks & 1][nb], acc[mb][nb], 0, 0, 0);
;       __builtin_amdgcn_s_setprio(0);
;       __builtin_amdgcn_sched_barrier(0);
;     }
.Lstg723_w1:
	s_waitcnt lgkmcnt(0)
	s_barrier
	s_cmp_eq_u32 s50, 0
	s_cbranch_scc1 .Lstg723_skip
	s_setprio 1
	v_mfma_f32_32x32x16_f16 v[48:63], v[84:87], v[76:79], v[48:63]
	v_mfma_f32_32x32x16_f16 v[32:47], v[88:91], v[76:79], v[32:47]
	v_mfma_f32_32x32x16_f16 v[16:31], v[84:87], v[80:83], v[16:31]
	v_mfma_f32_32x32x16_f16 v[0:15], v[88:91], v[80:83], v[0:15]
	v_mfma_f32_32x32x16_f16 v[48:63], v[100:103], v[92:95], v[48:63]
	v_mfma_f32_32x32x16_f16 v[32:47], v[104:107], v[92:95], v[32:47]
	v_mfma_f32_32x32x16_f16 v[16:31], v[100:103], v[96:99], v[16:31]
	v_mfma_f32_32x32x16_f16 v[0:15], v[104:107], v[96:99], v[0:15]
	s_setprio 0
.Lstg723_skip:
	v_add_u32_e32 v80, v75, v73
	v_add_u32_e32 v88, v114, v73
	v_add_u32_e32 v96, v75, v72
	v_add_u32_e32 v104, v114, v72
	ds_read_b128 v[76:79], v80
	ds_read_b128 v[80:83], v80 offset:4096
	ds_read_b128 v[84:87], v88 offset:16384
	ds_read_b128 v[88:91], v88 offset:20480
	ds_read_b128 v[92:95], v96
	ds_read_b128 v[96:99], v96 offset:4096
	ds_read_b128 v[100:103], v104 offset:16384
	ds_read_b128 v[104:107], v104 offset:20480
	s_cmp_lt_u32 s50, 0x700
	s_cbranch_scc0 .Lstg723_d0
	global_load_lds_dwordx4 v[108:109], off
	s_mov_b32 m0, s24
	v_lshl_add_u64 v[108:109], v[66:67], 0, s[50:51]
	global_load_lds_dwordx4 v[110:111], off
	v_lshl_add_u64 v[110:111], v[108:109], 0, s[52:53]
.Lstg723_d0:
	s_setprio 1
	s_waitcnt lgkmcnt(0)
	v_mfma_f32_32x32x16_f16 v[48:63], v[84:87], v[76:79], v[48:63]
	v_mfma_f32_32x32x16_f16 v[32:47], v[88:91], v[76:79], v[32:47]
	v_mfma_f32_32x32x16_f16 v[16:31], v[84:87], v[80:83], v[16:31]
	v_mfma_f32_32x32x16_f16 v[0:15], v[88:91], v[80:83], v[0:15]
	s_setprio 0
	v_add_u32_e32 v117, 0x4000, v115
	v_add_u32_e32 v116, 0x6000, v115
	v_readfirstlane_b32 s24, v117
	v_add_u32_e32 v80, v75, v71
	v_add_u32_e32 v88, v114, v71
	s_mov_b32 m0, s24
	v_readfirstlane_b32 s24, v116
	ds_read_b128 v[76:79], v80
	ds_read_b128 v[80:83], v80 offset:4096
	ds_read_b128 v[84:87], v88 offset:16384
	ds_read_b128 v[88:91], v88 offset:20480
	v_lshl_add_u64 v[112:113], v[108:109], 0, s[58:59]
	s_cmp_lt_u32 s50, 0x700
	s_cbranch_scc0 .Lstg723_d1
	global_load_lds_dwordx4 v[110:111], off
	s_mov_b32 m0, s24
	s_nop 0
	global_load_lds_dwordx4 v[112:113], off
.Lstg723_d1:
	s_setprio 1
	v_mfma_f32_32x32x16_f16 v[48:63], v[100:103], v[92:95], v[48:63]
	v_mfma_f32_32x32x16_f16 v[32:47], v[104:107], v[92:95], v[32:47]
	v_mfma_f32_32x32x16_f16 v[16:31], v[100:103], v[96:99], v[16:31]
	v_mfma_f32_32x32x16_f16 v[0:15], v[104:107], v[96:99], v[0:15]
	s_setprio 0
	v_add_u32_e32 v75, v75, v69
	ds_read_b128 v[92:95], v75
	ds_read_b128 v[96:99], v75 offset:4096
	v_add_u32_e32 v75, v114, v69
	v_add_u32_e32 v112, 0x8000, v115
	ds_read_b128 v[100:103], v75 offset:16384
	ds_read_b128 v[104:107], v75 offset:20480
	v_add_u32_e32 v75, 0xa000, v115
	v_readfirstlane_b32 s24, v112
	v_lshl_add_u64 v[110:111], v[108:109], 0, s[60:61]
	v_lshl_add_u64 v[108:109], v[108:109], 0, s[62:63]
	s_mov_b32 m0, s24
	v_readfirstlane_b32 s24, v75
	s_cmp_lt_u32 s50, 0x700
	s_cbranch_scc0 .Lstg723_d2
	global_load_lds_dwordx4 v[108:109], off
	s_mov_b32 m0, s24
	s_nop 0
	global_load_lds_dwordx4 v[110:111], off
.Lstg723_d2:
	s_add_i32 s24, s3, 1
	s_cmp_lg_u32 s3, 2
	s_cselect_b32 s3, s24, 0
	s_add_u32 s50, s50, 0x80
	s_addc_u32 s51, s51, 0
	s_cmp_eq_u32 s50, 0x800
	s_cbranch_scc0 .Lstg723_top
	s_waitcnt lgkmcnt(0)
	s_setprio 1
	v_mfma_f32_32x32x16_f16 v[48:63], v[84:87], v[76:79], v[48:63]
	v_mfma_f32_32x32x16_f16 v[32:47], v[88:91], v[76:79], v[32:47]
	v_mfma_f32_32x32x16_f16 v[16:31], v[84:87], v[80:83], v[16:31]
	v_mfma_f32_32x32x16_f16 v[0:15], v[88:91], v[80:83], v[0:15]
	v_mfma_f32_32x32x16_f16 v[48:63], v[100:103], v[92:95], v[48:63]
	v_mfma_f32_32x32x16_f16 v[32:47], v[104:107], v[92:95], v[32:47]
	v_mfma_f32_32x32x16_f16 v[16:31], v[100:103], v[96:99], v[16:31]
	v_mfma_f32_32x32x16_f16 v[0:15], v[104:107], v[96:99], v[0:15]
	s_setprio 0
	s_add_i32 s3, 0, 0x18000
	s_branch .Lstg723_end

; DI int otid() { int t = threadIdx.x; asm volatile("" : "+v"(t)); return t; }
; template <int MB>
; DI void out_tile(const Params& P, int layer, int row0, int nt, char* smem) {
;     ...
;   const int tid = otid(), lane = tid & 63, w = tid >> 6, wr = w >> 2, wc = w & 3, r32 = lane & 31, hh = lane >> 5;
; #pragma unroll
;   for (int mb = 0; mb < MB; ++mb) {
;     const int row = row0 + wr * 32 * MB + mb * 32 + r32;
;     const float* src; float* dst; int b;
;     if (row < T_LAT) { b = row >> 11; src = (layer == 0 ? P.x : P.out) + (size_t)row * D; dst = P.out + (size_t)row * D; }
;     else { const int rc = row - T_LAT; b = 16; src = (layer == 0 ? P.ctx : ctxw) + (size_t)rc * D; dst = ctxw + (size_t)rc * D; }
;     const float* gt = mods + b * 3072 + 2048;
.Lstg723_end:
	v_mov_b32_e32 v70, v208
	s_barrier
	s_nop 0
	v_ashrrev_i32_e32 v64, 2, v70
	v_and_b32_e32 v64, 0xffffffc0, v64
	v_and_or_b32 v65, v70, 31, s2
	v_add_u32_e32 v64, v65, v64
	s_movk_i32 s2, 0x7fff
	v_cmp_lt_i32_e32 vcc, s2, v64
	s_and_saveexec_b64 s[2:3], vcc
	s_xor_b64 s[2:3], exec, s[2:3]
	s_cbranch_execz .LBB0_726
	v_readlane_b32 s48, v253, 1
	v_add_u32_e32 v128, 0xffff8000, v64
	v_readlane_b32 s49, v253, 2
	v_lshlrev_b64 v[68:69], 12, v[128:129]
	v_readlane_b32 s62, v253, 15
	v_readlane_b32 s63, v253, 16
	v_readlane_b32 s48, v255, 30
	v_lshl_add_u64 v[66:67], s[42:43], 0, v[68:69]
	v_readlane_b32 s50, v253, 3
	v_readlane_b32 s51, v253, 4
	v_readlane_b32 s52, v253, 5
	v_readlane_b32 s53, v253, 6
	v_readlane_b32 s54, v253, 7
	v_readlane_b32 s55, v253, 8
	v_readlane_b32 s56, v253, 9
	v_readlane_b32 s57, v253, 10
	v_readlane_b32 s58, v253, 11
	v_readlane_b32 s59, v253, 12
	v_readlane_b32 s60, v253, 13
	v_readlane_b32 s61, v253, 14
	v_readlane_b32 s49, v255, 31
	v_lshl_add_u64 v[72:73], s[62:63], 0, v[68:69]
